# P4: batch + interleave the two o-accumulator MFMA chains and the score chain LDS reads (both block copies) on top of v53
# baseline (speedup 1.0000x reference)
; __device__ __forceinline__ unsigned cvt_pk_bf16(float lo, float hi) { const cvt_f2 v = {lo, hi}; return __builtin_bit_cast(unsigned, __builtin_convertvector(v, cvt_b2)); }
; #define LAS __attribute__((address_space(3)))
;     ...
;             if (w < 3 && !(VAR & 2)) {
;                 const int tb = w > 0 ? 1 : 0, sb = w > 1 ? 1 : 0; f32x4 pa = (f32x4){0.f, 0.f, 0.f, 0.f};
; #pragma unroll
;                 for (int kk = 0; kk < 4; ++kk) { const bf16x8_t a = *(const LAS bf16x8_t*)(QA + (16 * tb + fr) * 136 + 32 * kk + 8 * q); const bf16x8_t b = *(const LAS bf16x8_t*)(KA + (16 * sb + fr) * 136 + 32 * kk + 8 * q);
;                     pa = __builtin_amdgcn_mfma_f32_16x16x32_bf16(a, b, pa, 0, 0, 0); }
; #pragma unroll
;                 for (int r = 0; r < 4; r += 2) { const int t = 16 * tb + 4 * q + r, s_ = 16 * sb + fr; const unsigned pw = cvt_pk_bf16(s_ <= t ? pa[r] : 0.f, s_ <= t + 1 ? pa[r + 1] : 0.f);
;                     Pm[t * 40 + s_] = (bf16)pw; Pm[(t + 1) * 40 + s_] = (bf16)(pw >> 16); }
;             }
;             if (!(VAR & 4))
; #pragma unroll
;             for (int tb = 0; tb < 2; ++tb)
; #pragma unroll
;                 for (int kk = 0; kk < 4; ++kk) { const bf16x8_t a = *(const LAS bf16x8_t*)(QA + (16 * tb + fr) * 136 + 32 * kk + 8 * q); const bf16x8_t b = *(const LAS bf16x8_t*)(ST + (16 * w + fr) * 136 + 32 * kk + 8 * q);
;                     oacc[tb] = __builtin_amdgcn_mfma_f32_16x16x32_bf16(a, b, oacc[tb], 0, 0, 0); }
;         }
; #pragma unroll
;         for (int kb = 0; kb < 8; ++kb) { const f32x4 d4 = *(const LAS f32x4*)(DEC + 16 * kb + 4 * q); const bf16x8_t a = *(const LAS bf16x8_t*)(KDT + (16 * kb + fr) * 40 + 8 * q);
;             S[kb] = __builtin_amdgcn_mfma_f32_16x16x32_bf16(a, bV, S[kb] * d4, 0, 0, 0); }
.LBB0_584:
	ds_read_b128 v[104:107], v174 offset:27648
	v_cndmask_b32_e64 v108, 0, 1, s[90:91]
	v_cmp_ne_u32_e64 s[26:27], 1, v108
	s_andn2_b64 vcc, exec, s[90:91]
	s_cbranch_vccnz .LBB0_586
	ds_read_b128 v[108:111], v175
	ds_read_b128 v[112:115], v176 offset:8704
	ds_read_b128 v[218:221], v175 offset:64
	ds_read_b128 v[222:225], v176 offset:8768
	ds_read_b128 v[226:229], v175 offset:128
	ds_read_b128 v[230:233], v176 offset:8832
	ds_read_b128 v[234:237], v175 offset:192
	ds_read_b128 v[238:241], v176 offset:8896
	s_waitcnt lgkmcnt(6)
	v_mfma_f32_16x16x32_bf16 v[108:111], v[108:111], v[112:115], 0
	s_waitcnt lgkmcnt(4)
	v_mfma_f32_16x16x32_bf16 v[108:111], v[218:221], v[222:225], v[108:111]
	s_waitcnt lgkmcnt(2)
	v_mfma_f32_16x16x32_bf16 v[108:111], v[226:229], v[230:233], v[108:111]
	s_waitcnt lgkmcnt(0)
	v_mfma_f32_16x16x32_bf16 v[108:111], v[234:237], v[238:241], v[108:111]
	s_nop 7
	v_cndmask_b32_e64 v108, v108, 0, s[12:13]
	v_cndmask_b32_e64 v109, v109, 0, s[14:15]
	v_cvt_pk_bf16_f32 v108, v108, v109
	ds_write_b16 v177, v108
	ds_write_b16_d16_hi v177, v108 offset:80
	v_cndmask_b32_e64 v108, v110, 0, s[16:17]
	v_cndmask_b32_e64 v109, v111, 0, s[18:19]
	v_cvt_pk_bf16_f32 v108, v108, v109
	ds_write_b16 v177, v108 offset:160
	ds_write_b16_d16_hi v177, v108 offset:240
.LBB0_586:
	v_add_u32_e32 v188, v154, v153
	ds_read_b128 v[108:111], v178
	ds_read_b128 v[112:115], v188 offset:37888
	ds_read_b128 v[238:241], v178 offset:4352
	ds_read_b128 v[190:193], v178 offset:64
	ds_read_b128 v[194:197], v188 offset:37952
	ds_read_b128 v[218:221], v178 offset:4416
	ds_read_b128 v[230:233], v178 offset:128
	ds_read_b128 v[204:207], v188 offset:38016
	ds_read_b128 v[222:225], v178 offset:4480
	ds_read_b128 v[234:237], v178 offset:192
	ds_read_b128 v[208:211], v188 offset:38080
	ds_read_b128 v[226:229], v178 offset:4544
	v_add_u32_e32 v186, 0, v155
	s_waitcnt lgkmcnt(10)
	v_mfma_f32_16x16x32_bf16 v[108:111], v[108:111], v[112:115], 0
	s_waitcnt lgkmcnt(9)
	v_mfma_f32_16x16x32_bf16 v[112:115], v[238:241], v[112:115], 0
	s_waitcnt lgkmcnt(7)
	v_mfma_f32_16x16x32_bf16 v[108:111], v[190:193], v[194:197], v[108:111]
	s_waitcnt lgkmcnt(6)
	v_mfma_f32_16x16x32_bf16 v[112:115], v[218:221], v[194:197], v[112:115]
	s_waitcnt lgkmcnt(4)
	v_mfma_f32_16x16x32_bf16 v[108:111], v[230:233], v[204:207], v[108:111]
	s_waitcnt lgkmcnt(3)
	v_mfma_f32_16x16x32_bf16 v[112:115], v[222:225], v[204:207], v[112:115]
	s_waitcnt lgkmcnt(1)
	v_mfma_f32_16x16x32_bf16 v[108:111], v[234:237], v[208:211], v[108:111]
	s_waitcnt lgkmcnt(0)
	v_mfma_f32_16x16x32_bf16 v[112:115], v[226:229], v[208:211], v[112:115]
	v_add_u32_e32 v191, 0x12e00, v186
	v_add_u32_e32 v190, 0x12e40, v186
	v_add_u32_e32 v192, 0x12e80, v186
	v_add_u32_e32 v193, 0x12ec0, v186
	ds_read_b128 v[218:221], v191
	ds_read_b128 v[222:225], v179 offset:17408
	ds_read_b128 v[226:229], v190
	ds_read_b128 v[230:233], v179 offset:18688
	ds_read_b128 v[234:237], v192
	ds_read_b128 v[238:241], v179 offset:19968
	ds_read_b128 v[248:251], v193
	ds_read_b128 v[252:255], v179 offset:21248
	v_add_u32_e32 v194, 0x12f00, v186
	v_add_u32_e32 v195, 0x12f40, v186
	v_add_u32_e32 v196, 0x12f80, v186
	v_add_u32_e32 v197, 0x12fc0, v186
	s_waitcnt lgkmcnt(7)
	v_pk_mul_f32 v[36:37], v[36:37], v[220:221]
	v_pk_mul_f32 v[34:35], v[34:35], v[218:219]
	s_waitcnt lgkmcnt(6)
	s_nop 0
	v_mfma_f32_16x16x32_bf16 v[34:37], v[222:225], v[104:107], v[34:37]
	ds_read_b128 v[218:221], v194
	ds_read_b128 v[222:225], v179 offset:22528
	s_waitcnt lgkmcnt(7)
	v_pk_mul_f32 v[40:41], v[40:41], v[228:229]
	v_pk_mul_f32 v[38:39], v[38:39], v[226:227]
	s_waitcnt lgkmcnt(6)
	s_nop 0
	v_mfma_f32_16x16x32_bf16 v[38:41], v[230:233], v[104:107], v[38:41]
	ds_read_b128 v[226:229], v195
	ds_read_b128 v[230:233], v179 offset:23808
	s_waitcnt lgkmcnt(7)
	v_pk_mul_f32 v[44:45], v[44:45], v[236:237]
	v_pk_mul_f32 v[42:43], v[42:43], v[234:235]
	s_waitcnt lgkmcnt(6)
	s_nop 0
	v_mfma_f32_16x16x32_bf16 v[42:45], v[238:241], v[104:107], v[42:45]
	ds_read_b128 v[234:237], v196
	ds_read_b128 v[238:241], v179 offset:25088
	s_waitcnt lgkmcnt(7)
	v_pk_mul_f32 v[48:49], v[48:49], v[250:251]
	v_pk_mul_f32 v[46:47], v[46:47], v[248:249]
	s_waitcnt lgkmcnt(6)
	s_nop 0
	v_mfma_f32_16x16x32_bf16 v[46:49], v[252:255], v[104:107], v[46:49]
	ds_read_b128 v[204:207], v197
	ds_read_b128 v[208:211], v179 offset:26368
	s_waitcnt lgkmcnt(7)
	v_pk_mul_f32 v[52:53], v[52:53], v[220:221]
	v_pk_mul_f32 v[50:51], v[50:51], v[218:219]
	s_waitcnt lgkmcnt(6)
	s_nop 0
	v_mfma_f32_16x16x32_bf16 v[50:53], v[222:225], v[104:107], v[50:53]
	s_waitcnt lgkmcnt(5)
	v_pk_mul_f32 v[56:57], v[56:57], v[228:229]
	v_pk_mul_f32 v[54:55], v[54:55], v[226:227]
	s_waitcnt lgkmcnt(4)
	s_nop 0
	v_mfma_f32_16x16x32_bf16 v[54:57], v[230:233], v[104:107], v[54:57]
	s_waitcnt lgkmcnt(3)
	v_pk_mul_f32 v[60:61], v[60:61], v[236:237]
	v_pk_mul_f32 v[58:59], v[58:59], v[234:235]
	s_waitcnt lgkmcnt(2)
	s_nop 0
	v_mfma_f32_16x16x32_bf16 v[58:61], v[238:241], v[104:107], v[58:61]
	s_waitcnt lgkmcnt(0)
	s_barrier
; #define LAS __attribute__((address_space(3)))
;     ...
;             S[kb] = __builtin_amdgcn_mfma_f32_16x16x32_bf16(a, bV, S[kb] * d4, 0, 0, 0); }
;         __syncthreads();
;         if (FULL) {
; #pragma unroll
;             for (int tb = 0; tb < 2; ++tb) { const bf16x8_t a = *(const LAS bf16x8_t*)(Pm + (16 * tb + fr) * 40 + 8 * q); oacc[tb] = __builtin_amdgcn_mfma_f32_16x16x32_bf16(a, bV, oacc[tb], 0, 0, 0); }
;             if (VAR & 1) { asm volatile("" :: "v"(oacc[0]), "v"(oacc[1])); } else {
;             float ssv[8];
; #pragma unroll
;             for (int tb = 0; tb < 2; ++tb)
; #pragma unroll
;                 for (int r = 0; r < 4; ++r) ssv[tb * 4 + r] = dpp_xor_sum16(oacc[tb][r] * oacc[tb][r]);
;             if (fr == 0) {
; #pragma unroll
;                 for (int tb = 0; tb < 2; ++tb)
; #pragma unroll
;                     for (int r = 0; r < 4; ++r) SSQ[(16 * tb + 4 * q + r) * 8 + w] = ssv[tb * 4 + r]; }
	v_pk_mul_f32 v[64:65], v[64:65], v[206:207]
	v_pk_mul_f32 v[62:63], v[62:63], v[204:205]
	ds_read_b128 v[204:207], v180
	s_waitcnt lgkmcnt(0)
	v_mfma_f32_16x16x32_bf16 v[108:111], v[204:207], v[104:107], v[108:111]
	ds_read_b128 v[204:207], v180 offset:1280
	s_nop 6
	v_mul_f32_e32 v189, v111, v111
	v_mfma_f32_16x16x32_bf16 v[62:65], v[208:211], v[104:107], v[62:65]
	s_nop 0
	v_mov_b32_dpp v189, v189 quad_perm:[1,0,3,2] row_mask:0xf bank_mask:0xf bound_ctrl:1
	v_fmac_f32_e32 v189, v111, v111
	v_mul_f32_e32 v186, v110, v110
	s_waitcnt lgkmcnt(0)
	v_mfma_f32_16x16x32_bf16 v[104:107], v[204:207], v[104:107], v[112:115]
	v_add_f32_dpp v189, v189, v189 quad_perm:[2,3,0,1] row_mask:0xf bank_mask:0xf bound_ctrl:1
	v_mov_b32_dpp v186, v186 quad_perm:[1,0,3,2] row_mask:0xf bank_mask:0xf bound_ctrl:1
	s_nop 0
	v_mul_f32_e32 v112, v108, v108
	v_add_f32_dpp v204, v189, v189 row_half_mirror row_mask:0xf bank_mask:0xf bound_ctrl:1
	s_nop 2
	v_mul_f32_e32 v189, v104, v104
	v_mul_f32_e32 v114, v109, v109
	v_mov_b32_dpp v112, v112 quad_perm:[1,0,3,2] row_mask:0xf bank_mask:0xf bound_ctrl:1
	v_mov_b32_dpp v189, v189 quad_perm:[1,0,3,2] row_mask:0xf bank_mask:0xf bound_ctrl:1
	v_fmac_f32_e32 v189, v104, v104
	v_mov_b32_dpp v114, v114 quad_perm:[1,0,3,2] row_mask:0xf bank_mask:0xf bound_ctrl:1
	v_fmac_f32_e32 v112, v108, v108
	v_add_f32_dpp v189, v189, v189 quad_perm:[2,3,0,1] row_mask:0xf bank_mask:0xf bound_ctrl:1
	v_fmac_f32_e32 v114, v109, v109
	v_fmac_f32_e32 v186, v110, v110
	v_add_f32_dpp v206, v189, v189 row_half_mirror row_mask:0xf bank_mask:0xf bound_ctrl:1
	v_mul_f32_e32 v189, v105, v105
	v_add_f32_dpp v112, v112, v112 quad_perm:[2,3,0,1] row_mask:0xf bank_mask:0xf bound_ctrl:1
	v_add_f32_dpp v114, v114, v114 quad_perm:[2,3,0,1] row_mask:0xf bank_mask:0xf bound_ctrl:1
	v_mov_b32_dpp v189, v189 quad_perm:[1,0,3,2] row_mask:0xf bank_mask:0xf bound_ctrl:1
	v_fmac_f32_e32 v189, v105, v105
	v_add_f32_dpp v186, v186, v186 quad_perm:[2,3,0,1] row_mask:0xf bank_mask:0xf bound_ctrl:1
	v_add_f32_dpp v112, v112, v112 row_half_mirror row_mask:0xf bank_mask:0xf bound_ctrl:1
	v_add_f32_dpp v189, v189, v189 quad_perm:[2,3,0,1] row_mask:0xf bank_mask:0xf bound_ctrl:1
	v_add_f32_dpp v114, v114, v114 row_half_mirror row_mask:0xf bank_mask:0xf bound_ctrl:1
	v_add_f32_dpp v186, v186, v186 row_half_mirror row_mask:0xf bank_mask:0xf bound_ctrl:1
	v_add_f32_dpp v208, v189, v189 row_half_mirror row_mask:0xf bank_mask:0xf bound_ctrl:1
	v_mul_f32_e32 v189, v106, v106
	v_mov_b32_dpp v113, v112 row_mirror row_mask:0xf bank_mask:0xf bound_ctrl:1
	v_mov_b32_dpp v115, v114 row_mirror row_mask:0xf bank_mask:0xf bound_ctrl:1
	v_mov_b32_dpp v189, v189 quad_perm:[1,0,3,2] row_mask:0xf bank_mask:0xf bound_ctrl:1
	v_fmac_f32_e32 v189, v106, v106
	v_mov_b32_dpp v203, v186 row_mirror row_mask:0xf bank_mask:0xf bound_ctrl:1
	v_mov_b32_dpp v205, v204 row_mirror row_mask:0xf bank_mask:0xf bound_ctrl:1
	v_add_f32_dpp v189, v189, v189 quad_perm:[2,3,0,1] row_mask:0xf bank_mask:0xf bound_ctrl:1
	v_mov_b32_dpp v207, v206 row_mirror row_mask:0xf bank_mask:0xf bound_ctrl:1
	v_mov_b32_dpp v209, v208 row_mirror row_mask:0xf bank_mask:0xf bound_ctrl:1
	v_add_f32_dpp v210, v189, v189 row_half_mirror row_mask:0xf bank_mask:0xf bound_ctrl:1
	v_mul_f32_e32 v189, v107, v107
	s_nop 0
	v_mov_b32_dpp v211, v210 row_mirror row_mask:0xf bank_mask:0xf bound_ctrl:1
	v_mov_b32_dpp v189, v189 quad_perm:[1,0,3,2] row_mask:0xf bank_mask:0xf bound_ctrl:1
	v_fmac_f32_e32 v189, v107, v107
	s_nop 1
	v_add_f32_dpp v189, v189, v189 quad_perm:[2,3,0,1] row_mask:0xf bank_mask:0xf bound_ctrl:1
	s_nop 1
	v_add_f32_dpp v212, v189, v189 row_half_mirror row_mask:0xf bank_mask:0xf bound_ctrl:1
	v_add_u32_e32 v189, s3, v156
	s_nop 0
	v_mov_b32_dpp v213, v212 row_mirror row_mask:0xf bank_mask:0xf bound_ctrl:1
	s_and_saveexec_b64 vcc, s[10:11]
	s_cbranch_execz .LBB0_588
	v_add_f32_e32 v114, v114, v115
	v_add_f32_e32 v112, v112, v113
	v_add_f32_e32 v212, v212, v213
	v_add_f32_e32 v210, v210, v211
	v_add_f32_e32 v208, v208, v209
	v_add_f32_e32 v206, v206, v207
	v_add_f32_e32 v204, v204, v205
	v_add_f32_e32 v186, v186, v203
	ds_write2_b32 v189, v112, v114 offset1:8
	ds_write2_b32 v189, v186, v204 offset0:16 offset1:24
	ds_write2_b32 v189, v206, v208 offset0:128 offset1:136
	ds_write2_b32 v189, v210, v212 offset0:144 offset1:152

; __device__ __forceinline__ unsigned cvt_pk_bf16(float lo, float hi) { const cvt_f2 v = {lo, hi}; return __builtin_bit_cast(unsigned, __builtin_convertvector(v, cvt_b2)); }
; #define LAS __attribute__((address_space(3)))
;     ...
;             if (w < 3 && !(VAR & 2)) {
;                 const int tb = w > 0 ? 1 : 0, sb = w > 1 ? 1 : 0; f32x4 pa = (f32x4){0.f, 0.f, 0.f, 0.f};
; #pragma unroll
;                 for (int kk = 0; kk < 4; ++kk) { const bf16x8_t a = *(const LAS bf16x8_t*)(QA + (16 * tb + fr) * 136 + 32 * kk + 8 * q); const bf16x8_t b = *(const LAS bf16x8_t*)(KA + (16 * sb + fr) * 136 + 32 * kk + 8 * q);
;                     pa = __builtin_amdgcn_mfma_f32_16x16x32_bf16(a, b, pa, 0, 0, 0); }
; #pragma unroll
;                 for (int r = 0; r < 4; r += 2) { const int t = 16 * tb + 4 * q + r, s_ = 16 * sb + fr; const unsigned pw = cvt_pk_bf16(s_ <= t ? pa[r] : 0.f, s_ <= t + 1 ? pa[r + 1] : 0.f);
;                     Pm[t * 40 + s_] = (bf16)pw; Pm[(t + 1) * 40 + s_] = (bf16)(pw >> 16); }
;             }
;             if (!(VAR & 4))
; #pragma unroll
;             for (int tb = 0; tb < 2; ++tb)
; #pragma unroll
;                 for (int kk = 0; kk < 4; ++kk) { const bf16x8_t a = *(const LAS bf16x8_t*)(QA + (16 * tb + fr) * 136 + 32 * kk + 8 * q); const bf16x8_t b = *(const LAS bf16x8_t*)(ST + (16 * w + fr) * 136 + 32 * kk + 8 * q);
;                     oacc[tb] = __builtin_amdgcn_mfma_f32_16x16x32_bf16(a, b, oacc[tb], 0, 0, 0); }
;         }
; #pragma unroll
;         for (int kb = 0; kb < 8; ++kb) { const f32x4 d4 = *(const LAS f32x4*)(DEC + 16 * kb + 4 * q); const bf16x8_t a = *(const LAS bf16x8_t*)(KDT + (16 * kb + fr) * 40 + 8 * q);
;             S[kb] = __builtin_amdgcn_mfma_f32_16x16x32_bf16(a, bV, S[kb] * d4, 0, 0, 0); }
.LBB0_629:
	ds_read_b128 v[104:107], v174 offset:27648
	s_and_b64 vcc, exec, s[26:27]
	s_cbranch_vccnz .LBB0_631
	ds_read_b128 v[108:111], v175
	ds_read_b128 v[112:115], v176 offset:8704
	ds_read_b128 v[218:221], v175 offset:64
	ds_read_b128 v[222:225], v176 offset:8768
	ds_read_b128 v[226:229], v175 offset:128
	ds_read_b128 v[230:233], v176 offset:8832
	ds_read_b128 v[234:237], v175 offset:192
	ds_read_b128 v[238:241], v176 offset:8896
	s_waitcnt lgkmcnt(6)
	v_mfma_f32_16x16x32_bf16 v[108:111], v[108:111], v[112:115], 0
	s_waitcnt lgkmcnt(4)
	v_mfma_f32_16x16x32_bf16 v[108:111], v[218:221], v[222:225], v[108:111]
	s_waitcnt lgkmcnt(2)
	v_mfma_f32_16x16x32_bf16 v[108:111], v[226:229], v[230:233], v[108:111]
	s_waitcnt lgkmcnt(0)
	v_mfma_f32_16x16x32_bf16 v[108:111], v[234:237], v[238:241], v[108:111]
	s_nop 7
	v_cndmask_b32_e64 v108, v108, 0, s[12:13]
	v_cndmask_b32_e64 v109, v109, 0, s[14:15]
	v_cvt_pk_bf16_f32 v108, v108, v109
	ds_write_b16 v177, v108
	ds_write_b16_d16_hi v177, v108 offset:80
	v_cndmask_b32_e64 v108, v110, 0, s[16:17]
	v_cndmask_b32_e64 v109, v111, 0, s[18:19]
	v_cvt_pk_bf16_f32 v108, v108, v109
	ds_write_b16 v177, v108 offset:160
	ds_write_b16_d16_hi v177, v108 offset:240
.LBB0_631:
	ds_read_b128 v[108:111], v178
	ds_read_b128 v[112:115], v188 offset:37888
	ds_read_b128 v[238:241], v178 offset:4352
	ds_read_b128 v[202:205], v178 offset:64
	ds_read_b128 v[206:209], v188 offset:37952
	ds_read_b128 v[218:221], v178 offset:4416
	ds_read_b128 v[230:233], v178 offset:128
	ds_read_b128 v[210:213], v188 offset:38016
	ds_read_b128 v[222:225], v178 offset:4480
	ds_read_b128 v[234:237], v178 offset:192
	ds_read_b128 v[214:217], v188 offset:38080
	ds_read_b128 v[226:229], v178 offset:4544
	s_waitcnt lgkmcnt(10)
	v_mfma_f32_16x16x32_bf16 v[108:111], v[108:111], v[112:115], 0
	s_waitcnt lgkmcnt(9)
	v_mfma_f32_16x16x32_bf16 v[112:115], v[238:241], v[112:115], 0
	s_waitcnt lgkmcnt(7)
	v_mfma_f32_16x16x32_bf16 v[108:111], v[202:205], v[206:209], v[108:111]
	s_waitcnt lgkmcnt(6)
	v_mfma_f32_16x16x32_bf16 v[112:115], v[218:221], v[206:209], v[112:115]
	s_waitcnt lgkmcnt(4)
	v_mfma_f32_16x16x32_bf16 v[108:111], v[230:233], v[210:213], v[108:111]
	s_waitcnt lgkmcnt(3)
	v_mfma_f32_16x16x32_bf16 v[112:115], v[222:225], v[210:213], v[112:115]
	s_waitcnt lgkmcnt(1)
	v_mfma_f32_16x16x32_bf16 v[108:111], v[234:237], v[214:217], v[108:111]
	s_waitcnt lgkmcnt(0)
	v_mfma_f32_16x16x32_bf16 v[112:115], v[226:229], v[214:217], v[112:115]
	ds_read_b128 v[218:221], v191
	ds_read_b128 v[222:225], v179 offset:17408
	ds_read_b128 v[226:229], v190
	ds_read_b128 v[230:233], v179 offset:18688
	ds_read_b128 v[234:237], v192
	ds_read_b128 v[238:241], v179 offset:19968
	ds_read_b128 v[248:251], v193
	ds_read_b128 v[252:255], v179 offset:21248
	s_waitcnt lgkmcnt(7)
	v_pk_mul_f32 v[36:37], v[36:37], v[220:221]
	v_pk_mul_f32 v[34:35], v[34:35], v[218:219]
	s_waitcnt lgkmcnt(6)
	s_nop 0
	v_mfma_f32_16x16x32_bf16 v[34:37], v[222:225], v[104:107], v[34:37]
	ds_read_b128 v[218:221], v194
	ds_read_b128 v[222:225], v179 offset:22528
	s_waitcnt lgkmcnt(7)
	v_pk_mul_f32 v[40:41], v[40:41], v[228:229]
	v_pk_mul_f32 v[38:39], v[38:39], v[226:227]
	s_waitcnt lgkmcnt(6)
	s_nop 0
	v_mfma_f32_16x16x32_bf16 v[38:41], v[230:233], v[104:107], v[38:41]
	ds_read_b128 v[226:229], v195
	ds_read_b128 v[230:233], v179 offset:23808
	s_waitcnt lgkmcnt(7)
	v_pk_mul_f32 v[44:45], v[44:45], v[236:237]
	v_pk_mul_f32 v[42:43], v[42:43], v[234:235]
	s_waitcnt lgkmcnt(6)
	s_nop 0
	v_mfma_f32_16x16x32_bf16 v[42:45], v[238:241], v[104:107], v[42:45]
	ds_read_b128 v[190:193], v196
	ds_read_b128 v[202:205], v179 offset:25088
	s_waitcnt lgkmcnt(7)
	v_pk_mul_f32 v[48:49], v[48:49], v[250:251]
	v_pk_mul_f32 v[46:47], v[46:47], v[248:249]
	s_waitcnt lgkmcnt(6)
	s_nop 0
	v_mfma_f32_16x16x32_bf16 v[46:49], v[252:255], v[104:107], v[46:49]
	ds_read_b128 v[234:237], v197
	ds_read_b128 v[194:197], v179 offset:26368
	s_waitcnt lgkmcnt(7)
	v_pk_mul_f32 v[52:53], v[52:53], v[220:221]
	v_pk_mul_f32 v[50:51], v[50:51], v[218:219]
	s_waitcnt lgkmcnt(6)
	s_nop 0
	v_mfma_f32_16x16x32_bf16 v[50:53], v[222:225], v[104:107], v[50:53]
	s_waitcnt lgkmcnt(5)
	v_pk_mul_f32 v[56:57], v[56:57], v[228:229]
	v_pk_mul_f32 v[54:55], v[54:55], v[226:227]
	s_waitcnt lgkmcnt(4)
	s_nop 0
	v_mfma_f32_16x16x32_bf16 v[54:57], v[230:233], v[104:107], v[54:57]
	s_waitcnt lgkmcnt(3)
	v_pk_mul_f32 v[60:61], v[60:61], v[192:193]
	v_pk_mul_f32 v[58:59], v[58:59], v[190:191]
	s_waitcnt lgkmcnt(0)
	s_barrier
; #define LAS __attribute__((address_space(3)))
;     ...
;             S[kb] = __builtin_amdgcn_mfma_f32_16x16x32_bf16(a, bV, S[kb] * d4, 0, 0, 0); }
;         __syncthreads();
;         if (FULL) {
; #pragma unroll
;             for (int tb = 0; tb < 2; ++tb) { const bf16x8_t a = *(const LAS bf16x8_t*)(Pm + (16 * tb + fr) * 40 + 8 * q); oacc[tb] = __builtin_amdgcn_mfma_f32_16x16x32_bf16(a, bV, oacc[tb], 0, 0, 0); }
;             if (VAR & 1) { asm volatile("" :: "v"(oacc[0]), "v"(oacc[1])); } else {
;             float ssv[8];
; #pragma unroll
;             for (int tb = 0; tb < 2; ++tb)
; #pragma unroll
;                 for (int r = 0; r < 4; ++r) ssv[tb * 4 + r] = dpp_xor_sum16(oacc[tb][r] * oacc[tb][r]);
;             if (fr == 0) {
; #pragma unroll
;                 for (int tb = 0; tb < 2; ++tb)
; #pragma unroll
;                     for (int r = 0; r < 4; ++r) SSQ[(16 * tb + 4 * q + r) * 8 + w] = ssv[tb * 4 + r]; }
	v_pk_mul_f32 v[64:65], v[64:65], v[236:237]
	v_pk_mul_f32 v[62:63], v[62:63], v[234:235]
	ds_read_b128 v[190:193], v180
	s_waitcnt lgkmcnt(0)
	v_mfma_f32_16x16x32_bf16 v[108:111], v[190:193], v[104:107], v[108:111]
	ds_read_b128 v[190:193], v180 offset:1280
	s_nop 6
	v_mul_f32_e32 v188, v110, v110
	v_mfma_f32_16x16x32_bf16 v[58:61], v[202:205], v[104:107], v[58:61]
	s_nop 0
	v_mov_b32_dpp v188, v188 quad_perm:[1,0,3,2] row_mask:0xf bank_mask:0xf bound_ctrl:1
	v_fmac_f32_e32 v188, v110, v110
	v_mfma_f32_16x16x32_bf16 v[62:65], v[194:197], v[104:107], v[62:65]
	s_nop 0
	v_add_f32_dpp v188, v188, v188 quad_perm:[2,3,0,1] row_mask:0xf bank_mask:0xf bound_ctrl:1
	s_waitcnt lgkmcnt(0)
	v_mfma_f32_16x16x32_bf16 v[104:107], v[190:193], v[104:107], v[112:115]
	v_mul_f32_e32 v191, v111, v111
	v_add_f32_dpp v188, v188, v188 row_half_mirror row_mask:0xf bank_mask:0xf bound_ctrl:1
	s_nop 0
	v_mul_f32_e32 v112, v108, v108
	v_mul_f32_e32 v114, v109, v109
	s_nop 2
	v_mul_f32_e32 v193, v104, v104
	v_mul_f32_e32 v195, v105, v105
	v_mul_f32_e32 v197, v106, v106
	v_mul_f32_e32 v203, v107, v107
	v_mov_b32_dpp v112, v112 quad_perm:[1,0,3,2] row_mask:0xf bank_mask:0xf bound_ctrl:1
	v_mov_b32_dpp v114, v114 quad_perm:[1,0,3,2] row_mask:0xf bank_mask:0xf bound_ctrl:1
	v_mov_b32_dpp v191, v191 quad_perm:[1,0,3,2] row_mask:0xf bank_mask:0xf bound_ctrl:1
	v_mov_b32_dpp v193, v193 quad_perm:[1,0,3,2] row_mask:0xf bank_mask:0xf bound_ctrl:1
	v_mov_b32_dpp v195, v195 quad_perm:[1,0,3,2] row_mask:0xf bank_mask:0xf bound_ctrl:1
	v_mov_b32_dpp v197, v197 quad_perm:[1,0,3,2] row_mask:0xf bank_mask:0xf bound_ctrl:1
	v_mov_b32_dpp v203, v203 quad_perm:[1,0,3,2] row_mask:0xf bank_mask:0xf bound_ctrl:1
	v_fmac_f32_e32 v112, v108, v108
	v_fmac_f32_e32 v114, v109, v109
	v_fmac_f32_e32 v191, v111, v111
	v_fmac_f32_e32 v193, v104, v104
	v_fmac_f32_e32 v195, v105, v105
	v_fmac_f32_e32 v197, v106, v106
	v_fmac_f32_e32 v203, v107, v107
	v_add_f32_dpp v112, v112, v112 quad_perm:[2,3,0,1] row_mask:0xf bank_mask:0xf bound_ctrl:1
	v_add_f32_dpp v114, v114, v114 quad_perm:[2,3,0,1] row_mask:0xf bank_mask:0xf bound_ctrl:1
	v_add_f32_dpp v191, v191, v191 quad_perm:[2,3,0,1] row_mask:0xf bank_mask:0xf bound_ctrl:1
	v_add_f32_dpp v193, v193, v193 quad_perm:[2,3,0,1] row_mask:0xf bank_mask:0xf bound_ctrl:1
	v_add_f32_dpp v195, v195, v195 quad_perm:[2,3,0,1] row_mask:0xf bank_mask:0xf bound_ctrl:1
	v_add_f32_dpp v197, v197, v197 quad_perm:[2,3,0,1] row_mask:0xf bank_mask:0xf bound_ctrl:1
	v_add_f32_dpp v203, v203, v203 quad_perm:[2,3,0,1] row_mask:0xf bank_mask:0xf bound_ctrl:1
	v_add_f32_dpp v112, v112, v112 row_half_mirror row_mask:0xf bank_mask:0xf bound_ctrl:1
	v_add_f32_dpp v114, v114, v114 row_half_mirror row_mask:0xf bank_mask:0xf bound_ctrl:1
	v_add_f32_dpp v191, v191, v191 row_half_mirror row_mask:0xf bank_mask:0xf bound_ctrl:1
	v_add_f32_dpp v193, v193, v193 row_half_mirror row_mask:0xf bank_mask:0xf bound_ctrl:1
	v_add_f32_dpp v195, v195, v195 row_half_mirror row_mask:0xf bank_mask:0xf bound_ctrl:1
	v_add_f32_dpp v197, v197, v197 row_half_mirror row_mask:0xf bank_mask:0xf bound_ctrl:1
	v_add_f32_dpp v203, v203, v203 row_half_mirror row_mask:0xf bank_mask:0xf bound_ctrl:1
	v_mov_b32_dpp v113, v112 row_mirror row_mask:0xf bank_mask:0xf bound_ctrl:1
	v_mov_b32_dpp v115, v114 row_mirror row_mask:0xf bank_mask:0xf bound_ctrl:1
	v_mov_b32_dpp v190, v188 row_mirror row_mask:0xf bank_mask:0xf bound_ctrl:1
	v_mov_b32_dpp v192, v191 row_mirror row_mask:0xf bank_mask:0xf bound_ctrl:1
	v_mov_b32_dpp v194, v193 row_mirror row_mask:0xf bank_mask:0xf bound_ctrl:1
	v_mov_b32_dpp v196, v195 row_mirror row_mask:0xf bank_mask:0xf bound_ctrl:1
	v_mov_b32_dpp v202, v197 row_mirror row_mask:0xf bank_mask:0xf bound_ctrl:1
	v_mov_b32_dpp v204, v203 row_mirror row_mask:0xf bank_mask:0xf bound_ctrl:1
	s_and_saveexec_b64 s[26:27], s[10:11]
	s_cbranch_execz .LBB0_633
	v_add_f32_e32 v114, v114, v115
	v_add_f32_e32 v112, v112, v113
	v_add_f32_e32 v203, v203, v204
	v_add_f32_e32 v197, v197, v202
	v_add_f32_e32 v195, v195, v196
	v_add_f32_e32 v193, v193, v194
	v_add_f32_e32 v191, v191, v192
	v_add_f32_e32 v188, v188, v190
	ds_write2_b32 v189, v112, v114 offset1:8
	ds_write2_b32 v189, v188, v191 offset0:16 offset1:24
	ds_write2_b32 v189, v193, v195 offset0:128 offset1:136
	ds_write2_b32 v189, v197, v203 offset0:144 offset1:152
